# v21: v20 + pop-ahead of the next queue item inside latent attention items
# speedup vs baseline: 1.0716x; 1.0025x over previous
.LBB0_479:
	s_or_b64 exec, exec, s[10:11]
	v_mov_b32_e32 v235, 0
	v_readlane_b32 s14, v255, 14
	s_cmp_lg_u32 s14, 3
	s_cselect_b64 s[10:11], -1, 0
	v_readlane_b32 s15, v255, 15
	v_writelane_b32 v255, s10, 18
	v_cvt_f32_u32_e32 v1, s14
	v_mul_f32_e32 v1, 0xbe99999a, v1
	v_writelane_b32 v255, s11, 19
	s_lshl_b32 s10, s14, 6
	s_mov_b32 s6, s10
	s_mov_b32 s11, s31
	v_writelane_b32 v255, s6, 20
	s_lshl_b64 s[10:11], s[10:11], 2
	v_mul_f32_e32 v2, 0x3fb8aa3b, v1
	v_writelane_b32 v255, s7, 21
	v_readlane_b32 s6, v254, 21
	s_add_u32 s10, s6, s10
	v_readlane_b32 s6, v254, 22
	s_addc_u32 s11, s6, s11
	v_writelane_b32 v255, s10, 22
	s_cmp_eq_u32 s14, 3
	s_cselect_b32 s6, 0, 16
	v_writelane_b32 v255, s11, 23
	s_mov_b64 s[10:11], s[0:1]
	s_cselect_b32 s10, 0, 64
	s_or_b32 s11, s6, 64
	v_writelane_b32 v255, s11, 24
	s_add_i32 s11, s11, s10
	v_writelane_b32 v255, s11, 25
	s_addk_i32 s11, 0x280
	v_writelane_b32 v255, s11, 26
	s_add_i32 s11, s11, s6
	v_writelane_b32 v255, s11, 27
	s_add_i32 s11, s11, s6
	v_writelane_b32 v255, s11, 28
	s_add_i32 s11, s11, s6
	s_add_i32 s18, s11, 0x180
	v_writelane_b32 v255, s18, 29
	s_add_i32 s18, s11, 0x280
	v_writelane_b32 v255, s18, 30
	v_writelane_b32 v255, s11, 31
	s_add_i32 s34, s11, 0x380
	s_mov_b32 s11, 0x3fb8aa3b
	v_fma_f32 v3, v1, s11, -v2
	v_rndne_f32_e32 v4, v2
	v_fmac_f32_e32 v3, 0x32a5705f, v1
	v_sub_f32_e32 v2, v2, v4
	v_add_f32_e32 v2, v2, v3
	v_exp_f32_e32 v2, v2
	v_cvt_i32_f32_e32 v3, v4
	s_lshl_b64 s[26:27], s[14:15], 12
	v_writelane_b32 v255, s26, 32
	s_mov_b32 s11, 0xc2ce8ed0
	v_ldexp_f32 v2, v2, v3
	v_writelane_b32 v255, s27, 33
	s_mul_i32 s26, s14, 0x3c00
	s_mov_b32 s27, s31
	v_writelane_b32 v255, s26, 34
	v_cmp_ngt_f32_e32 vcc, s11, v1
	s_mov_b32 s11, 0x42b17218
	v_writelane_b32 v255, s27, 35
	v_cndmask_b32_e32 v2, 0, v2, vcc
	v_cmp_nlt_f32_e32 vcc, s11, v1
	s_lshl_b32 s14, s14, 7
	s_mov_b32 s15, s31
	s_lshl_b32 s10, s10, 2
	s_lshl_b32 s6, s6, 4
	v_cndmask_b32_e32 v1, v220, v2, vcc
	v_mov_b32_e32 v2, 0x3f4ccccd
	v_writelane_b32 v255, s14, 36
	s_add_i32 s10, s10, s6
	v_fmamk_f32 v236, v1, 0xbf19999a, v2
	v_writelane_b32 v255, s15, 37
	s_xor_b32 s6, s10, 0xffffeb01
	v_sub_f32_e32 v227, 1.0, v236
	v_writelane_b32 v255, s6, 38
	s_branch .LBB0_484

.LBB0_484:
	s_barrier
	v_readfirstlane_b32 s100, v235
	v_mov_b32_e32 v235, 0
	s_cmp_eq_u32 s100, 0
	s_cbranch_scc1 .Lpop_normal
	s_and_saveexec_b64 s[10:11], s[4:5]
	v_mov_b32_e32 v2, s16
	v_mov_b32_e32 v1, s101
	ds_write_b32 v2, v1
	s_branch .LBB0_488
.Lpop_normal:
	s_and_saveexec_b64 s[10:11], s[4:5]
	s_cbranch_execz .LBB0_488
	s_mov_b64 s[26:27], exec
	v_mbcnt_lo_u32_b32 v1, s26, 0
	v_mbcnt_hi_u32_b32 v1, s27, v1
	v_cmp_eq_u32_e32 vcc, 0, v1
	s_and_saveexec_b64 s[14:15], vcc
	s_cbranch_execz .LBB0_487
	s_bcnt1_i32_b64 s6, s[26:27]
	v_readlane_b32 s26, v255, 22
	s_waitcnt vmcnt(0)
	v_mov_b32_e32 v2, s6
	v_readlane_b32 s27, v255, 23
	s_nop 4
	global_atomic_add v2, v0, v2, s[26:27] sc0

.Lattn_nf_loop:
	s_and_b32 s10, s15, 1
	s_mul_i32 s6, s10, 0x8800
	v_add_u32_e32 v136, s6, v137
	v_add_u32_e32 v170, s6, v183
	s_sub_u32 s10, 0x8800, s6
	ds_read_b128 v[98:101], v136 offset:0
	ds_read_b128 v[102:105], v136 offset:64
	ds_read_b128 v[106:109], v136 offset:4352
	ds_read_b128 v[110:113], v136 offset:4416
	v_add_u32_e32 v171, s10, v126
	v_add_u32_e32 v173, s10, v127
	global_load_dwordx4 v[82:85], v124, s[64:65]
	global_load_dwordx4 v[86:89], v124, s[66:67]
	global_load_dwordx4 v[90:93], v124, s[68:69]
	global_load_dwordx4 v[94:97], v124, s[70:71]
	v_add_u32_e32 v124, s36, v124
	s_waitcnt lgkmcnt(3)
	v_mfma_f32_16x16x32_bf16 v[138:141], v[98:101], v[10:13], 0
	v_mfma_f32_16x16x32_bf16 v[142:145], v[98:101], v[14:17], 0
	s_waitcnt lgkmcnt(2)
	v_mfma_f32_16x16x32_bf16 v[138:141], v[102:105], v[2:5], v[138:141]
	v_mfma_f32_16x16x32_bf16 v[142:145], v[102:105], v[6:9], v[142:145]
	ds_read_b128 v[98:101], v136 offset:8704
	ds_read_b128 v[102:105], v136 offset:8768
	s_waitcnt lgkmcnt(3)
	v_mfma_f32_16x16x32_bf16 v[146:149], v[106:109], v[10:13], 0
	v_mfma_f32_16x16x32_bf16 v[150:153], v[106:109], v[14:17], 0
	s_waitcnt lgkmcnt(2)
	v_mfma_f32_16x16x32_bf16 v[146:149], v[110:113], v[2:5], v[146:149]
	v_mfma_f32_16x16x32_bf16 v[150:153], v[110:113], v[6:9], v[150:153]
	ds_read_b128 v[106:109], v136 offset:13056
	ds_read_b128 v[110:113], v136 offset:13120
	v_exp_f32_e32 v138, v138
	v_exp_f32_e32 v139, v139
	v_exp_f32_e32 v140, v140
	v_exp_f32_e32 v141, v141
	v_exp_f32_e32 v142, v142
	v_exp_f32_e32 v143, v143
	v_exp_f32_e32 v144, v144
	v_exp_f32_e32 v145, v145
	v_add_f32_e32 v123, v138, v123
	v_add_f32_e32 v122, v142, v122
	v_add_f32_e32 v123, v139, v123
	v_add_f32_e32 v122, v143, v122
	v_add_f32_e32 v123, v140, v123
	v_add_f32_e32 v122, v144, v122
	v_add_f32_e32 v123, v141, v123
	v_add_f32_e32 v122, v145, v122
	s_waitcnt lgkmcnt(3)
	v_mfma_f32_16x16x32_bf16 v[154:157], v[98:101], v[10:13], 0
	v_exp_f32_e32 v146, v146
	v_exp_f32_e32 v147, v147
	v_mfma_f32_16x16x32_bf16 v[158:161], v[98:101], v[14:17], 0
	v_exp_f32_e32 v148, v148
	v_exp_f32_e32 v149, v149
	s_waitcnt lgkmcnt(2)
	v_mfma_f32_16x16x32_bf16 v[154:157], v[102:105], v[2:5], v[154:157]
	v_exp_f32_e32 v150, v150
	v_exp_f32_e32 v151, v151
	v_mfma_f32_16x16x32_bf16 v[158:161], v[102:105], v[6:9], v[158:161]
	v_exp_f32_e32 v152, v152
	v_exp_f32_e32 v153, v153
	v_cvt_pk_bf16_f32 v114, v138, v139
	v_cvt_pk_bf16_f32 v115, v140, v141
	v_cvt_pk_bf16_f32 v118, v142, v143
	v_cvt_pk_bf16_f32 v119, v144, v145
	ds_read_b128 v[138:141], v170 offset:0
	ds_read_b128 v[142:145], v170 offset:4352
	s_waitcnt lgkmcnt(3)
	v_mfma_f32_16x16x32_bf16 v[162:165], v[106:109], v[10:13], 0
	v_add_f32_e32 v123, v146, v123
	v_add_f32_e32 v122, v150, v122
	v_add_f32_e32 v123, v147, v123
	v_mfma_f32_16x16x32_bf16 v[166:169], v[106:109], v[14:17], 0
	v_add_f32_e32 v122, v151, v122
	v_add_f32_e32 v123, v148, v123
	v_add_f32_e32 v122, v152, v122
	s_waitcnt lgkmcnt(2)
	v_mfma_f32_16x16x32_bf16 v[162:165], v[110:113], v[2:5], v[162:165]
	v_add_f32_e32 v123, v149, v123
	v_add_f32_e32 v122, v153, v122
	v_cvt_pk_bf16_f32 v116, v146, v147
	v_cvt_pk_bf16_f32 v117, v148, v149
	v_mfma_f32_16x16x32_bf16 v[166:169], v[110:113], v[6:9], v[166:169]
	v_cvt_pk_bf16_f32 v120, v150, v151
	v_cvt_pk_bf16_f32 v121, v152, v153
	ds_read_b128 v[146:149], v170 offset:8704
	ds_read_b128 v[150:153], v170 offset:13056
	ds_read_b128 v[98:101], v170 offset:17408
	ds_read_b128 v[102:105], v170 offset:21760
	ds_read_b128 v[106:109], v170 offset:26112
	ds_read_b128 v[110:113], v170 offset:30464
	v_exp_f32_e32 v154, v154
	v_exp_f32_e32 v155, v155
	v_exp_f32_e32 v156, v156
	v_exp_f32_e32 v157, v157
	v_exp_f32_e32 v158, v158
	v_exp_f32_e32 v159, v159
	v_exp_f32_e32 v160, v160
	v_exp_f32_e32 v161, v161
	s_waitcnt lgkmcnt(7)
	v_mfma_f32_16x16x32_bf16 v[78:81], v[138:141], v[114:117], v[78:81]
	v_mfma_f32_16x16x32_bf16 v[74:77], v[138:141], v[118:121], v[74:77]
	v_exp_f32_e32 v162, v162
	v_exp_f32_e32 v163, v163
	v_exp_f32_e32 v164, v164
	v_exp_f32_e32 v165, v165
	s_waitcnt lgkmcnt(6)
	v_mfma_f32_16x16x32_bf16 v[70:73], v[142:145], v[114:117], v[70:73]
	v_mfma_f32_16x16x32_bf16 v[62:65], v[142:145], v[118:121], v[62:65]
	v_exp_f32_e32 v166, v166
	v_exp_f32_e32 v167, v167
	v_exp_f32_e32 v168, v168
	v_exp_f32_e32 v169, v169
	s_waitcnt lgkmcnt(5)
	v_mfma_f32_16x16x32_bf16 v[66:69], v[146:149], v[114:117], v[66:69]
	v_mfma_f32_16x16x32_bf16 v[46:49], v[146:149], v[118:121], v[46:49]
	v_add_f32_e32 v123, v154, v123
	v_add_f32_e32 v122, v158, v122
	v_add_f32_e32 v123, v155, v123
	v_add_f32_e32 v122, v159, v122
	v_add_f32_e32 v123, v156, v123
	v_add_f32_e32 v122, v160, v122
	v_add_f32_e32 v123, v157, v123
	v_add_f32_e32 v122, v161, v122
	s_waitcnt lgkmcnt(4)
	v_mfma_f32_16x16x32_bf16 v[58:61], v[150:153], v[114:117], v[58:61]
	v_mfma_f32_16x16x32_bf16 v[38:41], v[150:153], v[118:121], v[38:41]
	ds_read_b128 v[138:141], v170 offset:17472
	ds_read_b128 v[142:145], v170 offset:21824
	ds_read_b128 v[146:149], v170 offset:26176
	ds_read_b128 v[150:153], v170 offset:30528
	v_cvt_pk_bf16_f32 v184, v154, v155
	v_cvt_pk_bf16_f32 v185, v156, v157
	v_cvt_pk_bf16_f32 v128, v158, v159
	v_cvt_pk_bf16_f32 v129, v160, v161
	s_waitcnt lgkmcnt(7)
	v_mfma_f32_16x16x32_bf16 v[54:57], v[98:101], v[114:117], v[54:57]
	v_mfma_f32_16x16x32_bf16 v[30:33], v[98:101], v[118:121], v[30:33]
	v_add_f32_e32 v123, v162, v123
	v_add_f32_e32 v122, v166, v122
	v_add_f32_e32 v123, v163, v123
	v_add_f32_e32 v122, v167, v122
	v_add_f32_e32 v123, v164, v123
	v_add_f32_e32 v122, v168, v122
	v_add_f32_e32 v123, v165, v123
	v_add_f32_e32 v122, v169, v122
	s_waitcnt lgkmcnt(6)
	v_mfma_f32_16x16x32_bf16 v[50:53], v[102:105], v[114:117], v[50:53]
	v_mfma_f32_16x16x32_bf16 v[26:29], v[102:105], v[118:121], v[26:29]
	v_cvt_pk_bf16_f32 v186, v162, v163
	v_cvt_pk_bf16_f32 v187, v164, v165
	v_cvt_pk_bf16_f32 v130, v166, v167
	v_cvt_pk_bf16_f32 v131, v168, v169
	ds_read_b128 v[154:157], v170 offset:64
	ds_read_b128 v[158:161], v170 offset:4416
	ds_read_b128 v[162:165], v170 offset:8768
	ds_read_b128 v[166:169], v170 offset:13120
	s_waitcnt lgkmcnt(9)
	v_mfma_f32_16x16x32_bf16 v[42:45], v[106:109], v[114:117], v[42:45]
	v_mfma_f32_16x16x32_bf16 v[22:25], v[106:109], v[118:121], v[22:25]
	s_waitcnt lgkmcnt(8)
	v_mfma_f32_16x16x32_bf16 v[34:37], v[110:113], v[114:117], v[34:37]
	v_mfma_f32_16x16x32_bf16 v[18:21], v[110:113], v[118:121], v[18:21]
	ds_read_b128 v[98:101], v136 offset:17408
	ds_read_b128 v[102:105], v136 offset:17472
	ds_read_b128 v[106:109], v136 offset:21760
	ds_read_b128 v[110:113], v136 offset:21824
	s_waitcnt lgkmcnt(7)
	v_mfma_f32_16x16x32_bf16 v[78:81], v[154:157], v[184:187], v[78:81]
	v_mfma_f32_16x16x32_bf16 v[74:77], v[154:157], v[128:131], v[74:77]
	s_waitcnt lgkmcnt(6)
	v_mfma_f32_16x16x32_bf16 v[70:73], v[158:161], v[184:187], v[70:73]
	v_mfma_f32_16x16x32_bf16 v[62:65], v[158:161], v[128:131], v[62:65]
	s_waitcnt vmcnt(3)
	ds_write_b128 v171, v[82:85] offset:0
	s_waitcnt vmcnt(2)
	ds_write_b128 v171, v[86:89] offset:8704
	s_waitcnt vmcnt(1)
	ds_write_b128 v171, v[90:93] offset:17408
	s_waitcnt vmcnt(0)
	ds_write_b128 v171, v[94:97] offset:26112
	s_waitcnt lgkmcnt(9)
	v_mfma_f32_16x16x32_bf16 v[66:69], v[162:165], v[184:187], v[66:69]
	v_mfma_f32_16x16x32_bf16 v[46:49], v[162:165], v[128:131], v[46:49]
	s_waitcnt lgkmcnt(8)
	v_mfma_f32_16x16x32_bf16 v[58:61], v[166:169], v[184:187], v[58:61]
	v_mfma_f32_16x16x32_bf16 v[38:41], v[166:169], v[128:131], v[38:41]
	global_load_dwordx4 v[82:85], v125, s[72:73]
	global_load_dwordx4 v[86:89], v125, s[74:75]
	global_load_dwordx4 v[90:93], v125, s[76:77]
	global_load_dwordx4 v[94:97], v125, s[78:79]
	v_add_u32_e32 v125, s38, v125
	v_mfma_f32_16x16x32_bf16 v[54:57], v[138:141], v[184:187], v[54:57]
	v_mfma_f32_16x16x32_bf16 v[30:33], v[138:141], v[128:131], v[30:33]
	v_mfma_f32_16x16x32_bf16 v[50:53], v[142:145], v[184:187], v[50:53]
	v_mfma_f32_16x16x32_bf16 v[26:29], v[142:145], v[128:131], v[26:29]
	v_mfma_f32_16x16x32_bf16 v[42:45], v[146:149], v[184:187], v[42:45]
	v_mfma_f32_16x16x32_bf16 v[22:25], v[146:149], v[128:131], v[22:25]
	v_mfma_f32_16x16x32_bf16 v[34:37], v[150:153], v[184:187], v[34:37]
	v_mfma_f32_16x16x32_bf16 v[18:21], v[150:153], v[128:131], v[18:21]
	s_waitcnt lgkmcnt(7)
	v_mfma_f32_16x16x32_bf16 v[138:141], v[98:101], v[10:13], 0
	v_mfma_f32_16x16x32_bf16 v[142:145], v[98:101], v[14:17], 0
	s_waitcnt lgkmcnt(6)
	v_mfma_f32_16x16x32_bf16 v[138:141], v[102:105], v[2:5], v[138:141]
	v_mfma_f32_16x16x32_bf16 v[142:145], v[102:105], v[6:9], v[142:145]
	ds_read_b128 v[98:101], v136 offset:26112
	ds_read_b128 v[102:105], v136 offset:26176
	s_waitcnt lgkmcnt(7)
	v_mfma_f32_16x16x32_bf16 v[146:149], v[106:109], v[10:13], 0
	v_mfma_f32_16x16x32_bf16 v[150:153], v[106:109], v[14:17], 0
	s_waitcnt lgkmcnt(6)
	v_mfma_f32_16x16x32_bf16 v[146:149], v[110:113], v[2:5], v[146:149]
	v_mfma_f32_16x16x32_bf16 v[150:153], v[110:113], v[6:9], v[150:153]
	ds_read_b128 v[106:109], v136 offset:30464
	ds_read_b128 v[110:113], v136 offset:30528
	v_exp_f32_e32 v138, v138
	v_exp_f32_e32 v139, v139
	v_exp_f32_e32 v140, v140
	v_exp_f32_e32 v141, v141
	v_exp_f32_e32 v142, v142
	v_exp_f32_e32 v143, v143
	v_exp_f32_e32 v144, v144
	v_exp_f32_e32 v145, v145
	v_add_f32_e32 v123, v138, v123
	v_add_f32_e32 v122, v142, v122
	v_add_f32_e32 v123, v139, v123
	v_add_f32_e32 v122, v143, v122
	v_add_f32_e32 v123, v140, v123
	v_add_f32_e32 v122, v144, v122
	v_add_f32_e32 v123, v141, v123
	v_add_f32_e32 v122, v145, v122
	s_waitcnt lgkmcnt(3)
	v_mfma_f32_16x16x32_bf16 v[154:157], v[98:101], v[10:13], 0
	v_exp_f32_e32 v146, v146
	v_exp_f32_e32 v147, v147
	v_mfma_f32_16x16x32_bf16 v[158:161], v[98:101], v[14:17], 0
	v_exp_f32_e32 v148, v148
	v_exp_f32_e32 v149, v149
	s_waitcnt lgkmcnt(2)
	v_mfma_f32_16x16x32_bf16 v[154:157], v[102:105], v[2:5], v[154:157]
	v_exp_f32_e32 v150, v150
	v_exp_f32_e32 v151, v151
	v_mfma_f32_16x16x32_bf16 v[158:161], v[102:105], v[6:9], v[158:161]
	v_exp_f32_e32 v152, v152
	v_exp_f32_e32 v153, v153
	v_cvt_pk_bf16_f32 v114, v138, v139
	v_cvt_pk_bf16_f32 v115, v140, v141
	v_cvt_pk_bf16_f32 v118, v142, v143
	v_cvt_pk_bf16_f32 v119, v144, v145
	ds_read_b128 v[138:141], v170 offset:128
	ds_read_b128 v[142:145], v170 offset:4480
	s_waitcnt lgkmcnt(3)
	v_mfma_f32_16x16x32_bf16 v[162:165], v[106:109], v[10:13], 0
	v_add_f32_e32 v123, v146, v123
	v_add_f32_e32 v122, v150, v122
	v_add_f32_e32 v123, v147, v123
	v_mfma_f32_16x16x32_bf16 v[166:169], v[106:109], v[14:17], 0
	v_add_f32_e32 v122, v151, v122
	v_add_f32_e32 v123, v148, v123
	v_add_f32_e32 v122, v152, v122
	s_waitcnt lgkmcnt(2)
	v_mfma_f32_16x16x32_bf16 v[162:165], v[110:113], v[2:5], v[162:165]
	v_add_f32_e32 v123, v149, v123
	v_add_f32_e32 v122, v153, v122
	v_cvt_pk_bf16_f32 v116, v146, v147
	v_cvt_pk_bf16_f32 v117, v148, v149
	v_mfma_f32_16x16x32_bf16 v[166:169], v[110:113], v[6:9], v[166:169]
	v_cvt_pk_bf16_f32 v120, v150, v151
	v_cvt_pk_bf16_f32 v121, v152, v153
	ds_read_b128 v[146:149], v170 offset:8832
	ds_read_b128 v[150:153], v170 offset:13184
	ds_read_b128 v[98:101], v170 offset:17536
	ds_read_b128 v[102:105], v170 offset:21888
	ds_read_b128 v[106:109], v170 offset:26240
	ds_read_b128 v[110:113], v170 offset:30592
	v_exp_f32_e32 v154, v154
	v_exp_f32_e32 v155, v155
	v_exp_f32_e32 v156, v156
	v_exp_f32_e32 v157, v157
	v_exp_f32_e32 v158, v158
	v_exp_f32_e32 v159, v159
	v_exp_f32_e32 v160, v160
	v_exp_f32_e32 v161, v161
	s_waitcnt lgkmcnt(7)
	v_mfma_f32_16x16x32_bf16 v[78:81], v[138:141], v[114:117], v[78:81]
	v_mfma_f32_16x16x32_bf16 v[74:77], v[138:141], v[118:121], v[74:77]
	v_exp_f32_e32 v162, v162
	v_exp_f32_e32 v163, v163
	v_exp_f32_e32 v164, v164
	v_exp_f32_e32 v165, v165
	s_waitcnt lgkmcnt(6)
	v_mfma_f32_16x16x32_bf16 v[70:73], v[142:145], v[114:117], v[70:73]
	v_mfma_f32_16x16x32_bf16 v[62:65], v[142:145], v[118:121], v[62:65]
	v_exp_f32_e32 v166, v166
	v_exp_f32_e32 v167, v167
	v_exp_f32_e32 v168, v168
	v_exp_f32_e32 v169, v169
	s_waitcnt lgkmcnt(5)
	v_mfma_f32_16x16x32_bf16 v[66:69], v[146:149], v[114:117], v[66:69]
	v_mfma_f32_16x16x32_bf16 v[46:49], v[146:149], v[118:121], v[46:49]
	v_add_f32_e32 v123, v154, v123
	v_add_f32_e32 v122, v158, v122
	v_add_f32_e32 v123, v155, v123
	v_add_f32_e32 v122, v159, v122
	v_add_f32_e32 v123, v156, v123
	v_add_f32_e32 v122, v160, v122
	v_add_f32_e32 v123, v157, v123
	v_add_f32_e32 v122, v161, v122
	s_waitcnt lgkmcnt(4)
	v_mfma_f32_16x16x32_bf16 v[58:61], v[150:153], v[114:117], v[58:61]
	v_mfma_f32_16x16x32_bf16 v[38:41], v[150:153], v[118:121], v[38:41]
	ds_read_b128 v[138:141], v170 offset:17600
	ds_read_b128 v[142:145], v170 offset:21952
	ds_read_b128 v[146:149], v170 offset:26304
	ds_read_b128 v[150:153], v170 offset:30656
	v_cvt_pk_bf16_f32 v184, v154, v155
	v_cvt_pk_bf16_f32 v185, v156, v157
	v_cvt_pk_bf16_f32 v128, v158, v159
	v_cvt_pk_bf16_f32 v129, v160, v161
	s_waitcnt lgkmcnt(7)
	v_mfma_f32_16x16x32_bf16 v[54:57], v[98:101], v[114:117], v[54:57]
	v_mfma_f32_16x16x32_bf16 v[30:33], v[98:101], v[118:121], v[30:33]
	v_add_f32_e32 v123, v162, v123
	v_add_f32_e32 v122, v166, v122
	v_add_f32_e32 v123, v163, v123
	v_add_f32_e32 v122, v167, v122
	v_add_f32_e32 v123, v164, v123
	v_add_f32_e32 v122, v168, v122
	v_add_f32_e32 v123, v165, v123
	v_add_f32_e32 v122, v169, v122
	s_waitcnt lgkmcnt(6)
	v_mfma_f32_16x16x32_bf16 v[50:53], v[102:105], v[114:117], v[50:53]
	v_mfma_f32_16x16x32_bf16 v[26:29], v[102:105], v[118:121], v[26:29]
	v_cvt_pk_bf16_f32 v186, v162, v163
	v_cvt_pk_bf16_f32 v187, v164, v165
	v_cvt_pk_bf16_f32 v130, v166, v167
	v_cvt_pk_bf16_f32 v131, v168, v169
	ds_read_b128 v[154:157], v170 offset:192
	ds_read_b128 v[158:161], v170 offset:4544
	ds_read_b128 v[162:165], v170 offset:8896
	ds_read_b128 v[166:169], v170 offset:13248
	s_waitcnt lgkmcnt(9)
	v_mfma_f32_16x16x32_bf16 v[42:45], v[106:109], v[114:117], v[42:45]
	v_mfma_f32_16x16x32_bf16 v[22:25], v[106:109], v[118:121], v[22:25]
	s_waitcnt lgkmcnt(8)
	v_mfma_f32_16x16x32_bf16 v[34:37], v[110:113], v[114:117], v[34:37]
	v_mfma_f32_16x16x32_bf16 v[18:21], v[110:113], v[118:121], v[18:21]
	s_waitcnt lgkmcnt(3)
	v_mfma_f32_16x16x32_bf16 v[78:81], v[154:157], v[184:187], v[78:81]
	v_mfma_f32_16x16x32_bf16 v[74:77], v[154:157], v[128:131], v[74:77]
	s_waitcnt lgkmcnt(2)
	v_mfma_f32_16x16x32_bf16 v[70:73], v[158:161], v[184:187], v[70:73]
	v_mfma_f32_16x16x32_bf16 v[62:65], v[158:161], v[128:131], v[62:65]
	s_waitcnt lgkmcnt(1)
	v_mfma_f32_16x16x32_bf16 v[66:69], v[162:165], v[184:187], v[66:69]
	v_mfma_f32_16x16x32_bf16 v[46:49], v[162:165], v[128:131], v[46:49]
	s_waitcnt lgkmcnt(0)
	v_mfma_f32_16x16x32_bf16 v[58:61], v[166:169], v[184:187], v[58:61]
	v_mfma_f32_16x16x32_bf16 v[38:41], v[166:169], v[128:131], v[38:41]
	s_waitcnt vmcnt(3)
	ds_write_b128 v173, v[82:85] offset:0
	s_waitcnt vmcnt(2)
	ds_write_b128 v173, v[86:89] offset:8704
	s_waitcnt vmcnt(1)
	ds_write_b128 v173, v[90:93] offset:17408
	s_waitcnt vmcnt(0)
	ds_write_b128 v173, v[94:97] offset:26112
	v_mfma_f32_16x16x32_bf16 v[54:57], v[138:141], v[184:187], v[54:57]
	v_mfma_f32_16x16x32_bf16 v[30:33], v[138:141], v[128:131], v[30:33]
	v_mfma_f32_16x16x32_bf16 v[50:53], v[142:145], v[184:187], v[50:53]
	v_mfma_f32_16x16x32_bf16 v[26:29], v[142:145], v[128:131], v[26:29]
	v_mfma_f32_16x16x32_bf16 v[42:45], v[146:149], v[184:187], v[42:45]
	v_mfma_f32_16x16x32_bf16 v[22:25], v[146:149], v[128:131], v[22:25]
	v_mfma_f32_16x16x32_bf16 v[34:37], v[150:153], v[184:187], v[34:37]
	v_mfma_f32_16x16x32_bf16 v[18:21], v[150:153], v[128:131], v[18:21]
	s_waitcnt lgkmcnt(0)
	s_barrier
	s_add_i32 s15, s15, 1
	s_cmp_eq_u32 s15, 33
	s_cbranch_scc0 .Lattn_nf_loop
	v_readlane_b32 s64, v175, 0
	v_readlane_b32 s65, v175, 1
	v_readlane_b32 s66, v175, 2
	v_readlane_b32 s67, v175, 3
	v_readlane_b32 s68, v175, 4
	v_readlane_b32 s69, v175, 5
	v_readlane_b32 s70, v175, 6
	v_readlane_b32 s71, v175, 7
	v_readlane_b32 s72, v175, 8
	v_readlane_b32 s73, v175, 9
	v_readlane_b32 s74, v175, 10
	v_readlane_b32 s75, v175, 11
	v_readlane_b32 s76, v175, 12
	v_readlane_b32 s77, v175, 13
	v_readlane_b32 s78, v175, 14
	v_readlane_b32 s79, v175, 15
	s_nop 4
	ds_read_b128 v[82:85], v137 offset:34816
	ds_read_b128 v[90:93], v137 offset:34880
	v_add_f32_e32 v186, v132, v134
	v_add_f32_e32 v184, v133, v135
	ds_bpermute_b32 v187, v172, v186
	ds_bpermute_b32 v185, v172, v184
	s_mov_b32 s10, 0x3fb8aa3b
	s_mov_b32 s11, 0xc2ce8ed0
	s_mov_b32 s6, 0x42b17218
	s_waitcnt lgkmcnt(3)
	v_mfma_f32_16x16x32_bf16 v[86:89], v[82:85], v[10:13], 0
	v_cmp_eq_u32_e64 s[40:41], 0, v179
	s_lshl_b32 s30, s14, 1
	v_lshlrev_b32_e32 v196, 3, v178
	v_mov_b32_e32 v197, 0
	v_lshlrev_b32_e32 v198, 4, v179
	v_or3_b32 v198, v198, v177, v180
	v_ashrrev_i32_e32 v199, 31, v198
	v_lshlrev_b64 v[198:199], 11, v[198:199]
	s_mov_b64 s[100:101], 0x18a10000
	v_lshl_add_u64 v[198:199], s[42:43], 0, v[198:199]
	v_lshl_add_u64 v[198:199], v[198:199], 0, s[30:31]
	v_lshl_add_u64 v[198:199], v[198:199], 0, v[196:197]
	v_lshl_add_u64 v[198:199], v[198:199], 0, s[100:101]
	global_load_dwordx2 v[146:147], v[198:199], off
	global_load_dwordx2 v[148:149], v[198:199], off offset:32
	global_load_dwordx2 v[150:151], v[198:199], off offset:64
	global_load_dwordx2 v[152:153], v[198:199], off offset:96
	global_load_dwordx2 v[188:189], v[198:199], off offset:128
	global_load_dwordx2 v[190:191], v[198:199], off offset:160
	global_load_dwordx2 v[192:193], v[198:199], off offset:192
	global_load_dwordx2 v[194:195], v[198:199], off offset:224
	s_mov_b64 s[100:101], exec
	s_and_b64 exec, exec, s[4:5]
	s_cbranch_execz .Lpop_skip
	v_readlane_b32 s14, v255, 22
	v_readlane_b32 s15, v255, 23
	v_mov_b32_e32 v224, 1
	s_nop 4
	global_atomic_add v224, v0, v224, s[14:15] sc0
.Lpop_skip:
	s_mov_b64 exec, s[100:101]
	v_mov_b32_e32 v235, 1
	s_load_dwordx2 s[100:101], s[44:45], 0x80
	v_readlane_b32 s14, v255, 36
	v_mfma_f32_16x16x32_bf16 v[82:85], v[82:85], v[14:17], 0
	ds_read_b128 v[98:101], v137 offset:39232
	v_readlane_b32 s15, v255, 37
	s_lshl_b64 s[14:15], s[14:15], 2
	s_waitcnt lgkmcnt(3)
	v_mfma_f32_16x16x32_bf16 v[86:89], v[90:93], v[2:5], v[86:89]
	ds_read_b128 v[142:145], v137 offset:47936
	v_mfma_f32_16x16x32_bf16 v[82:85], v[90:93], v[6:9], v[82:85]
	ds_read_b128 v[90:93], v137 offset:39168
	s_nop 4
	v_exp_f32_e32 v116, v86
	v_exp_f32_e32 v114, v87
	s_waitcnt lgkmcnt(0)
	v_mfma_f32_16x16x32_bf16 v[94:97], v[90:93], v[10:13], 0
	v_exp_f32_e32 v134, v82
	v_exp_f32_e32 v132, v83
	v_exp_f32_e32 v130, v84
	v_mfma_f32_16x16x32_bf16 v[90:93], v[90:93], v[14:17], 0
	v_exp_f32_e32 v128, v85
	ds_read_b128 v[82:85], v137 offset:43520
	v_exp_f32_e32 v112, v88
	v_mfma_f32_16x16x32_bf16 v[90:93], v[98:101], v[6:9], v[90:93]
	v_exp_f32_e32 v110, v89
	v_mfma_f32_16x16x32_bf16 v[94:97], v[98:101], v[2:5], v[94:97]
	s_nop 1
	v_cvt_pk_bf16_f32 v98, v134, v132
	s_nop 1
	s_nop 5
	v_exp_f32_e32 v126, v90
	v_exp_f32_e32 v124, v91
	v_exp_f32_e32 v120, v92
	v_exp_f32_e32 v118, v93
	ds_read_b128 v[90:93], v137 offset:43584
	s_waitcnt lgkmcnt(1)
	v_mfma_f32_16x16x32_bf16 v[86:89], v[82:85], v[10:13], 0
	v_exp_f32_e32 v108, v94
	v_exp_f32_e32 v106, v95
	v_exp_f32_e32 v104, v96
	v_mfma_f32_16x16x32_bf16 v[82:85], v[82:85], v[14:17], 0
	v_exp_f32_e32 v102, v97
	s_nop 1
	v_cvt_pk_bf16_f32 v94, v116, v114
	s_nop 1
	s_nop 1
	v_cvt_pk_bf16_f32 v95, v112, v110
	s_nop 1
	s_waitcnt lgkmcnt(0)
	v_mfma_f32_16x16x32_bf16 v[82:85], v[90:93], v[6:9], v[82:85]
	s_nop 1
	v_cvt_pk_bf16_f32 v96, v108, v106
	s_nop 1
	s_nop 1
	v_cvt_pk_bf16_f32 v97, v104, v102
	s_nop 1
	s_nop 1
	v_cvt_pk_bf16_f32 v99, v130, v128
	s_nop 1
	v_mfma_f32_16x16x32_bf16 v[86:89], v[90:93], v[2:5], v[86:89]
	ds_read_b128 v[90:93], v137 offset:47872
	s_nop 5
	v_exp_f32_e32 v135, v82
	v_exp_f32_e32 v133, v83
	v_exp_f32_e32 v131, v84
	v_exp_f32_e32 v129, v85
	ds_read_b128 v[82:85], v183 offset:34816
	s_nop 1
	v_cvt_pk_bf16_f32 v100, v126, v124
	s_nop 1
	s_nop 1
	v_cvt_pk_bf16_f32 v101, v120, v118
	s_nop 1
	s_waitcnt lgkmcnt(0)
	v_mfma_f32_16x16x32_bf16 v[78:81], v[82:85], v[94:97], v[78:81]
	v_exp_f32_e32 v117, v86
	v_exp_f32_e32 v115, v87
	v_exp_f32_e32 v113, v88
	v_mfma_f32_16x16x32_bf16 v[74:77], v[82:85], v[98:101], v[74:77]
	ds_read_b128 v[82:85], v183 offset:34880
	v_exp_f32_e32 v111, v89
	v_mfma_f32_16x16x32_bf16 v[138:141], v[90:93], v[10:13], 0
	v_mfma_f32_16x16x32_bf16 v[90:93], v[90:93], v[14:17], 0
	v_mfma_f32_16x16x32_bf16 v[90:93], v[142:145], v[6:9], v[90:93]
	v_mfma_f32_16x16x32_bf16 v[138:141], v[142:145], v[2:5], v[138:141]
	s_nop 1
	v_cvt_pk_bf16_f32 v142, v135, v133
	s_nop 1
	s_nop 6
	v_exp_f32_e32 v127, v90
	v_exp_f32_e32 v125, v91
	v_exp_f32_e32 v121, v92
	v_exp_f32_e32 v119, v93
	s_nop 1
	v_cvt_pk_bf16_f32 v143, v131, v129
	s_nop 1
	s_nop 1
	v_cvt_pk_bf16_f32 v144, v127, v125
	s_nop 1
	s_nop 1
	v_cvt_pk_bf16_f32 v145, v121, v119
	s_nop 1
	v_exp_f32_e32 v109, v138
	s_waitcnt lgkmcnt(0)
	v_mfma_f32_16x16x32_bf16 v[90:93], v[82:85], v[142:145], v[74:77]
	v_exp_f32_e32 v107, v139
	v_exp_f32_e32 v105, v140
	v_exp_f32_e32 v103, v141
	ds_read_b128 v[74:77], v183 offset:39168
	s_waitcnt lgkmcnt(0)
	v_mfma_f32_16x16x32_bf16 v[70:73], v[74:77], v[94:97], v[70:73]
	s_nop 1
	v_cvt_pk_bf16_f32 v138, v117, v115
	s_nop 1
	s_nop 1
	v_cvt_pk_bf16_f32 v139, v113, v111
	s_nop 1
	s_nop 1
	v_cvt_pk_bf16_f32 v140, v109, v107
	s_nop 1
	v_mfma_f32_16x16x32_bf16 v[62:65], v[74:77], v[98:101], v[62:65]
	ds_read_b128 v[74:77], v183 offset:39232
	s_nop 1
	v_cvt_pk_bf16_f32 v141, v105, v103
	s_nop 1
	s_waitcnt lgkmcnt(0)
	v_mfma_f32_16x16x32_bf16 v[86:89], v[74:77], v[142:145], v[62:65]
	s_nop 4
	ds_read_b128 v[62:65], v183 offset:43520
	s_waitcnt lgkmcnt(0)
	v_mfma_f32_16x16x32_bf16 v[66:69], v[62:65], v[94:97], v[66:69]
	v_mfma_f32_16x16x32_bf16 v[46:49], v[62:65], v[98:101], v[46:49]
	ds_read_b128 v[62:65], v183 offset:43584
	v_mfma_f32_16x16x32_bf16 v[78:81], v[82:85], v[138:141], v[78:81]
	v_mfma_f32_16x16x32_bf16 v[82:85], v[74:77], v[138:141], v[70:73]
	s_waitcnt lgkmcnt(0)
	v_mfma_f32_16x16x32_bf16 v[74:77], v[62:65], v[142:145], v[46:49]
	s_nop 2
	ds_read_b128 v[46:49], v183 offset:47872
	s_waitcnt lgkmcnt(0)
	v_mfma_f32_16x16x32_bf16 v[58:61], v[46:49], v[94:97], v[58:61]
	v_mfma_f32_16x16x32_bf16 v[38:41], v[46:49], v[98:101], v[38:41]
	ds_read_b128 v[46:49], v183 offset:47936
	v_mfma_f32_16x16x32_bf16 v[70:73], v[62:65], v[138:141], v[66:69]
	s_waitcnt lgkmcnt(0)
	v_mfma_f32_16x16x32_bf16 v[66:69], v[46:49], v[142:145], v[38:41]
	s_nop 3
	ds_read_b128 v[38:41], v183 offset:52224
	v_mfma_f32_16x16x32_bf16 v[62:65], v[46:49], v[138:141], v[58:61]
	s_waitcnt lgkmcnt(0)
	v_mfma_f32_16x16x32_bf16 v[46:49], v[38:41], v[94:97], v[54:57]
	v_mfma_f32_16x16x32_bf16 v[30:33], v[38:41], v[98:101], v[30:33]
	ds_read_b128 v[38:41], v183 offset:52288
	s_waitcnt lgkmcnt(0)
	v_mfma_f32_16x16x32_bf16 v[58:61], v[38:41], v[142:145], v[30:33]
	s_nop 4
	ds_read_b128 v[30:33], v183 offset:56576
	v_mfma_f32_16x16x32_bf16 v[54:57], v[38:41], v[138:141], v[46:49]
	s_waitcnt lgkmcnt(0)
	v_mfma_f32_16x16x32_bf16 v[38:41], v[30:33], v[94:97], v[50:53]
	s_nop 2
	ds_read_b128 v[50:53], v137 offset:52288
	v_mfma_f32_16x16x32_bf16 v[26:29], v[30:33], v[98:101], v[26:29]
	ds_read_b128 v[30:33], v183 offset:56640
	s_waitcnt lgkmcnt(0)
	v_mfma_f32_16x16x32_bf16 v[46:49], v[30:33], v[142:145], v[26:29]
	s_nop 4
	ds_read_b128 v[26:29], v183 offset:60928
	v_mfma_f32_16x16x32_bf16 v[38:41], v[30:33], v[138:141], v[38:41]
	s_waitcnt lgkmcnt(0)
	v_mfma_f32_16x16x32_bf16 v[30:33], v[26:29], v[94:97], v[42:45]
	s_nop 2
	ds_read_b128 v[42:45], v183 offset:60992
	v_mfma_f32_16x16x32_bf16 v[22:25], v[26:29], v[98:101], v[22:25]
	s_waitcnt lgkmcnt(0)
	v_mfma_f32_16x16x32_bf16 v[26:29], v[42:45], v[138:141], v[30:33]
	v_mfma_f32_16x16x32_bf16 v[30:33], v[42:45], v[142:145], v[22:25]
	ds_read_b128 v[42:45], v183 offset:65344
	s_nop 3
	ds_read_b128 v[22:25], v183 offset:65280
	s_waitcnt lgkmcnt(0)
	v_mfma_f32_16x16x32_bf16 v[34:37], v[22:25], v[94:97], v[34:37]
	v_mfma_f32_16x16x32_bf16 v[22:25], v[22:25], v[98:101], v[18:21]
	ds_read_b128 v[98:101], v137 offset:56640
	v_mfma_f32_16x16x32_bf16 v[18:21], v[42:45], v[138:141], v[34:37]
	s_nop 4
	ds_read_b128 v[34:37], v137 offset:52224
	v_mfma_f32_16x16x32_bf16 v[22:25], v[42:45], v[142:145], v[22:25]
	s_waitcnt lgkmcnt(0)
	v_mfma_f32_16x16x32_bf16 v[42:45], v[34:37], v[10:13], 0
	v_mfma_f32_16x16x32_bf16 v[34:37], v[34:37], v[14:17], 0
	v_mfma_f32_16x16x32_bf16 v[42:45], v[50:53], v[2:5], v[42:45]
	v_mfma_f32_16x16x32_bf16 v[34:37], v[50:53], v[6:9], v[34:37]
	ds_read_b128 v[50:53], v137 offset:56576
	s_nop 5
	v_exp_f32_e32 v158, v42
	v_exp_f32_e32 v156, v43
	s_waitcnt lgkmcnt(0)
	v_mfma_f32_16x16x32_bf16 v[94:97], v[50:53], v[10:13], 0
	v_exp_f32_e32 v172, v34
	v_exp_f32_e32 v174, v35
	v_pk_add_f32 v[34:35], v[134:135], 0 op_sel_hi:[1,0]
	v_mfma_f32_16x16x32_bf16 v[50:53], v[50:53], v[14:17], 0
	v_add_f32_e64 v34, v132, v34
	v_add_f32_e64 v35, v133, v35
	v_exp_f32_e32 v170, v36
	v_pk_add_f32 v[34:35], v[130:131], v[34:35]
	v_mfma_f32_16x16x32_bf16 v[50:53], v[98:101], v[6:9], v[50:53]
	v_add_f32_e64 v34, v128, v34
	v_add_f32_e64 v35, v129, v35
	v_exp_f32_e32 v166, v37
	v_pk_add_f32 v[34:35], v[34:35], v[126:127]
	v_exp_f32_e32 v154, v44
	v_pk_add_f32 v[34:35], v[124:125], v[34:35]
	s_nop 1
	v_exp_f32_e32 v168, v50
	v_pk_add_f32 v[34:35], v[120:121], v[34:35]
	v_exp_f32_e32 v164, v51
	v_pk_add_f32 v[118:119], v[118:119], v[34:35]
	ds_read_b128 v[34:37], v137 offset:60928
	v_exp_f32_e32 v160, v52
	v_exp_f32_e32 v162, v53
	ds_read_b128 v[50:53], v137 offset:60992
	v_exp_f32_e32 v144, v45
	s_waitcnt lgkmcnt(1)
	v_mfma_f32_16x16x32_bf16 v[42:45], v[34:37], v[10:13], 0
	v_mfma_f32_16x16x32_bf16 v[34:37], v[34:37], v[14:17], 0
	s_waitcnt lgkmcnt(0)
	v_mfma_f32_16x16x32_bf16 v[42:45], v[50:53], v[2:5], v[42:45]
	v_mfma_f32_16x16x32_bf16 v[34:37], v[50:53], v[6:9], v[34:37]
	ds_read_b128 v[50:53], v137 offset:65280
	s_nop 5
	v_exp_f32_e32 v159, v42
	v_exp_f32_e32 v157, v43
	s_waitcnt lgkmcnt(0)
	v_mfma_f32_16x16x32_bf16 v[10:13], v[50:53], v[10:13], 0
	v_exp_f32_e32 v173, v34
	v_exp_f32_e32 v175, v35
	v_exp_f32_e32 v171, v36
	v_mfma_f32_16x16x32_bf16 v[14:17], v[50:53], v[14:17], 0
	ds_read_b128 v[50:53], v137 offset:65344
	v_exp_f32_e32 v167, v37
	s_nop 1
	v_cvt_pk_bf16_f32 v128, v173, v175
	s_nop 1
	v_mfma_f32_16x16x32_bf16 v[94:97], v[98:101], v[2:5], v[94:97]
	s_nop 1
	v_cvt_pk_bf16_f32 v98, v172, v174
	s_nop 1
	s_nop 1
	v_cvt_pk_bf16_f32 v99, v170, v166
	s_nop 1
	s_nop 1
	v_cvt_pk_bf16_f32 v100, v168, v164
	s_nop 1
	s_waitcnt lgkmcnt(0)
	v_mfma_f32_16x16x32_bf16 v[2:5], v[50:53], v[2:5], v[10:13]
	s_nop 1
	v_cvt_pk_bf16_f32 v101, v160, v162
	s_nop 1
	s_nop 5
	v_exp_f32_e32 v142, v94
	ds_read_b128 v[10:13], v183 offset:35008
	v_exp_f32_e32 v143, v2
	v_exp_f32_e32 v141, v3
	v_exp_f32_e32 v139, v4
	v_exp_f32_e32 v137, v5
	ds_read_b128 v[2:5], v183 offset:34944
	v_mfma_f32_16x16x32_bf16 v[6:9], v[50:53], v[6:9], v[14:17]
	v_exp_f32_e32 v140, v95
	v_exp_f32_e32 v138, v96
	v_exp_f32_e32 v136, v97
	s_nop 1
	v_cvt_pk_bf16_f32 v94, v158, v156
	s_nop 1
	s_nop 1
	v_cvt_pk_bf16_f32 v95, v154, v144
	s_nop 1
	s_nop 1
	v_cvt_pk_bf16_f32 v96, v142, v140
	s_nop 1
	s_nop 1
	v_cvt_pk_bf16_f32 v97, v138, v136
	s_nop 1
	s_nop 4
	v_exp_f32_e32 v169, v6
	v_exp_f32_e32 v165, v7
	v_exp_f32_e32 v161, v8
	v_exp_f32_e32 v163, v9
	s_waitcnt lgkmcnt(0)
	v_mfma_f32_16x16x32_bf16 v[6:9], v[2:5], v[94:97], v[78:81]
	s_nop 1
	v_cvt_pk_bf16_f32 v129, v171, v167
	s_nop 1
	s_nop 1
	v_cvt_pk_bf16_f32 v130, v169, v165
	s_nop 1
	s_nop 1
	v_cvt_pk_bf16_f32 v131, v161, v163
	s_nop 1
	v_mfma_f32_16x16x32_bf16 v[2:5], v[2:5], v[98:101], v[90:93]
	v_exp_f32_e32 v155, v44
	v_exp_f32_e32 v145, v45
	s_nop 1
	v_cvt_pk_bf16_f32 v124, v159, v157
	s_nop 1
	v_mfma_f32_16x16x32_bf16 v[90:93], v[10:13], v[128:131], v[2:5]
	s_nop 1
	v_cvt_pk_bf16_f32 v125, v155, v145
	s_nop 1
	s_nop 1
	v_cvt_pk_bf16_f32 v126, v143, v141
	s_nop 1
	s_nop 1
	v_cvt_pk_bf16_f32 v127, v139, v137
	s_nop 1
	s_nop 0
	v_mfma_f32_16x16x32_bf16 v[78:81], v[10:13], v[124:127], v[6:9]
	s_nop 2
	ds_read_b128 v[2:5], v183 offset:39296
	ds_read_b128 v[10:13], v183 offset:39360
	s_waitcnt lgkmcnt(1)
	v_mfma_f32_16x16x32_bf16 v[6:9], v[2:5], v[94:97], v[82:85]
	v_mfma_f32_16x16x32_bf16 v[2:5], v[2:5], v[98:101], v[86:89]
	s_waitcnt lgkmcnt(0)
	v_mfma_f32_16x16x32_bf16 v[50:53], v[10:13], v[128:131], v[2:5]
	v_mfma_f32_16x16x32_bf16 v[14:17], v[10:13], v[124:127], v[6:9]
	s_nop 4
	ds_read_b128 v[2:5], v183 offset:43648
	ds_read_b128 v[10:13], v183 offset:43712
	s_waitcnt lgkmcnt(1)
	v_mfma_f32_16x16x32_bf16 v[6:9], v[2:5], v[94:97], v[70:73]
	v_mfma_f32_16x16x32_bf16 v[2:5], v[2:5], v[98:101], v[74:77]
	s_waitcnt lgkmcnt(0)
	v_mfma_f32_16x16x32_bf16 v[34:37], v[10:13], v[128:131], v[2:5]
	v_mfma_f32_16x16x32_bf16 v[6:9], v[10:13], v[124:127], v[6:9]
	s_nop 4
	ds_read_b128 v[2:5], v183 offset:48000
	s_waitcnt lgkmcnt(0)
	v_mfma_f32_16x16x32_bf16 v[10:13], v[2:5], v[94:97], v[62:65]
	s_nop 2
	ds_read_b128 v[62:65], v183 offset:48064
	v_mfma_f32_16x16x32_bf16 v[42:45], v[2:5], v[98:101], v[66:69]
	s_waitcnt lgkmcnt(0)
	v_mfma_f32_16x16x32_bf16 v[2:5], v[62:65], v[124:127], v[10:13]
	v_mfma_f32_16x16x32_bf16 v[10:13], v[62:65], v[128:131], v[42:45]
	ds_read_b128 v[62:65], v183 offset:52416
	s_nop 3
	ds_read_b128 v[42:45], v183 offset:52352
	s_waitcnt lgkmcnt(0)
	v_mfma_f32_16x16x32_bf16 v[54:57], v[42:45], v[94:97], v[54:57]
	v_mfma_f32_16x16x32_bf16 v[58:61], v[42:45], v[98:101], v[58:61]
	v_mfma_f32_16x16x32_bf16 v[42:45], v[62:65], v[124:127], v[54:57]
	v_mfma_f32_16x16x32_bf16 v[54:57], v[62:65], v[128:131], v[58:61]
	s_nop 5
	ds_read_b128 v[58:61], v183 offset:56704
	s_waitcnt lgkmcnt(0)
	v_mfma_f32_16x16x32_bf16 v[38:41], v[58:61], v[94:97], v[38:41]
	v_mfma_f32_16x16x32_bf16 v[46:49], v[58:61], v[98:101], v[46:49]
	ds_read_b128 v[58:61], v183 offset:56768
	s_waitcnt lgkmcnt(0)
	v_mfma_f32_16x16x32_bf16 v[38:41], v[58:61], v[124:127], v[38:41]
	v_mfma_f32_16x16x32_bf16 v[46:49], v[58:61], v[128:131], v[46:49]
	ds_read_b128 v[58:61], v183 offset:61056
	s_waitcnt lgkmcnt(0)
	v_mfma_f32_16x16x32_bf16 v[26:29], v[58:61], v[94:97], v[26:29]
	v_mfma_f32_16x16x32_bf16 v[30:33], v[58:61], v[98:101], v[30:33]
	ds_read_b128 v[58:61], v183 offset:61120
	s_waitcnt lgkmcnt(0)
	v_mfma_f32_16x16x32_bf16 v[26:29], v[58:61], v[124:127], v[26:29]
	v_mfma_f32_16x16x32_bf16 v[30:33], v[58:61], v[128:131], v[30:33]
	ds_read_b128 v[58:61], v183 offset:65408
	s_waitcnt lgkmcnt(0)
	v_mfma_f32_16x16x32_bf16 v[18:21], v[58:61], v[94:97], v[18:21]
	v_mfma_f32_16x16x32_bf16 v[22:25], v[58:61], v[98:101], v[22:25]
	ds_read_b128 v[58:61], v183 offset:65472
	s_waitcnt lgkmcnt(0)
	s_barrier
	v_mfma_f32_16x16x32_bf16 v[18:21], v[58:61], v[124:127], v[18:21]
	v_mfma_f32_16x16x32_bf16 v[22:25], v[58:61], v[128:131], v[22:25]
	v_add_f32_e64 v58, v172, 0
	v_add_f32_e64 v59, v173, 0
	v_add_f32_e32 v60, v122, v118
	v_pk_add_f32 v[58:59], v[174:175], v[58:59]
	v_add_f32_e32 v60, v60, v119
	v_pk_add_f32 v[58:59], v[170:171], v[58:59]
	s_nop 0
	v_pk_add_f32 v[58:59], v[166:167], v[58:59]
	s_nop 0
	v_pk_add_f32 v[58:59], v[58:59], v[168:169]
	s_nop 0
	v_pk_add_f32 v[58:59], v[164:165], v[58:59]
	s_nop 0
	v_pk_add_f32 v[58:59], v[160:161], v[58:59]
	s_nop 0
	v_pk_add_f32 v[58:59], v[162:163], v[58:59]
	s_nop 0
	v_add_f32_e32 v58, v60, v58
	v_pk_add_f32 v[60:61], v[116:117], 0 op_sel_hi:[1,0]
	v_add_f32_e32 v62, v58, v59
	v_pk_add_f32 v[60:61], v[114:115], v[60:61]
	v_pk_add_f32 v[58:59], v[158:159], 0 op_sel_hi:[1,0]
	v_pk_add_f32 v[60:61], v[112:113], v[60:61]
	v_pk_add_f32 v[58:59], v[156:157], v[58:59]
	v_pk_add_f32 v[60:61], v[110:111], v[60:61]
	v_pk_add_f32 v[58:59], v[154:155], v[58:59]
	v_pk_add_f32 v[60:61], v[60:61], v[108:109]
	v_pk_add_f32 v[58:59], v[144:145], v[58:59]
	v_pk_add_f32 v[60:61], v[106:107], v[60:61]
	v_pk_add_f32 v[58:59], v[58:59], v[142:143]
	v_pk_add_f32 v[60:61], v[104:105], v[60:61]
	v_pk_add_f32 v[58:59], v[140:141], v[58:59]
	v_pk_add_f32 v[60:61], v[102:103], v[60:61]
	v_pk_add_f32 v[58:59], v[138:139], v[58:59]
	v_add_f32_e32 v60, v123, v60
	v_pk_add_f32 v[58:59], v[136:137], v[58:59]
	v_add_f32_e32 v60, v60, v61
	v_add_f32_e32 v58, v60, v58
	v_add_f32_e32 v58, v58, v59
	v_add_f32_e32 v59, v186, v187
	v_mul_f32_e32 v60, 0x3fb8aa3b, v59
	v_fma_f32 v61, v59, s10, -v60
	v_rndne_f32_e32 v63, v60
	v_fmac_f32_e32 v61, 0x32a5705f, v59
	v_sub_f32_e32 v60, v60, v63
	v_add_f32_e32 v60, v60, v61
	v_exp_f32_e32 v60, v60
	v_cvt_i32_f32_e32 v61, v63
	v_cmp_ngt_f32_e32 vcc, s11, v59
	v_ldexp_f32 v60, v60, v61
	s_nop 0
	v_cndmask_b32_e32 v60, 0, v60, vcc
	v_cmp_nlt_f32_e32 vcc, s6, v59
	s_nop 1
	v_cndmask_b32_e32 v59, v220, v60, vcc
	v_add_f32_e32 v60, v184, v185
	v_mul_f32_e32 v61, 0x3fb8aa3b, v60
	v_fma_f32 v63, v60, s10, -v61
	v_rndne_f32_e32 v64, v61
	v_fmac_f32_e32 v63, 0x32a5705f, v60
	v_sub_f32_e32 v61, v61, v64
	v_add_f32_e32 v61, v61, v63
	v_exp_f32_e32 v61, v61
	v_cvt_i32_f32_e32 v63, v64
	v_cmp_ngt_f32_e32 vcc, s11, v60
	v_ldexp_f32 v61, v61, v63
	s_nop 0
	v_cndmask_b32_e32 v61, 0, v61, vcc
	v_cmp_nlt_f32_e32 vcc, s6, v60
	s_movk_i32 s6, 0x200
	s_nop 0
	v_cndmask_b32_e32 v60, v220, v61, vcc
	v_sub_f32_e32 v59, v59, v60
	ds_bpermute_b32 v60, v176, v58
	v_add_f32_e32 v59, v236, v59
	v_cndmask_b32_e64 v59, -v59, 1.0, s[40:41]
	s_waitcnt lgkmcnt(0)
	v_add_f32_e32 v58, v58, v60
	ds_bpermute_b32 v60, v1, v58
	s_waitcnt lgkmcnt(0)
	v_add_f32_e32 v58, v58, v60
	ds_bpermute_b32 v60, v176, v62
	s_waitcnt lgkmcnt(0)
	v_add_f32_e32 v60, v62, v60
	ds_bpermute_b32 v61, v1, v60
	s_waitcnt lgkmcnt(0)
	v_add_f32_e32 v60, v60, v61
	v_div_scale_f32 v61, s[10:11], v58, v58, v59
	v_rcp_f32_e32 v62, v61
	s_nop 0
	v_fma_f32 v63, -v61, v62, 1.0
	v_fmac_f32_e32 v62, v63, v62
	v_div_scale_f32 v63, vcc, v59, v58, v59
	v_mul_f32_e32 v64, v63, v62
	v_fma_f32 v65, -v61, v64, v63
	v_fmac_f32_e32 v64, v65, v62
	v_fma_f32 v61, -v61, v64, v63
	v_div_fmas_f32 v61, v61, v62, v64
	v_div_fixup_f32 v62, v61, v58, v59
	v_div_scale_f32 v58, s[10:11], v60, v60, v59
	v_rcp_f32_e32 v61, v58
	s_nop 0
	v_fma_f32 v63, -v58, v61, 1.0
	v_fmac_f32_e32 v61, v63, v61
	v_div_scale_f32 v63, vcc, v59, v60, v59
	v_mul_f32_e32 v64, v63, v61
	v_fma_f32 v65, -v58, v64, v63
	v_fmac_f32_e32 v64, v65, v61
	v_fma_f32 v58, -v58, v64, v63
	v_div_fmas_f32 v58, v58, v61, v64
	v_div_fixup_f32 v64, v58, v60, v59
	v_lshlrev_b32_e32 v58, 13, v182
	v_lshlrev_b32_e32 v59, 4, v181
	v_pk_mul_f32 v[66:67], v[90:91], v[64:65] op_sel_hi:[1,0]
	v_pk_mul_f32 v[68:69], v[92:93], v[64:65] op_sel_hi:[1,0]
	v_pk_mul_f32 v[70:71], v[78:79], v[62:63] op_sel_hi:[1,0]
	v_pk_mul_f32 v[72:73], v[80:81], v[62:63] op_sel_hi:[1,0]
	v_pk_mul_f32 v[74:75], v[10:11], v[64:65] op_sel_hi:[1,0]
	v_pk_mul_f32 v[76:77], v[12:13], v[64:65] op_sel_hi:[1,0]
	v_pk_mul_f32 v[78:79], v[2:3], v[62:63] op_sel_hi:[1,0]
	v_pk_mul_f32 v[80:81], v[4:5], v[62:63] op_sel_hi:[1,0]
	v_add3_u32 v84, 0, v58, v59
	v_cndmask_b32_e64 v61, v73, v69, s[40:41]
	v_cndmask_b32_e64 v60, v72, v68, s[40:41]
	v_cndmask_b32_e64 v59, v71, v67, s[40:41]
	v_cndmask_b32_e64 v58, v70, v66, s[40:41]
	v_cndmask_b32_e64 v5, v81, v77, s[40:41]
	v_cndmask_b32_e64 v4, v80, v76, s[40:41]
	v_cndmask_b32_e64 v3, v79, v75, s[40:41]
	v_cndmask_b32_e64 v2, v78, v74, s[40:41]
	v_pk_mul_f32 v[54:55], v[54:55], v[64:65] op_sel_hi:[1,0]
	v_pk_mul_f32 v[56:57], v[56:57], v[64:65] op_sel_hi:[1,0]
	v_pk_mul_f32 v[42:43], v[42:43], v[62:63] op_sel_hi:[1,0]
	v_pk_mul_f32 v[44:45], v[44:45], v[62:63] op_sel_hi:[1,0]
	ds_write_b128 v84, v[58:61]
	v_pk_mul_f32 v[50:51], v[50:51], v[64:65] op_sel_hi:[1,0]
	v_pk_mul_f32 v[52:53], v[52:53], v[64:65] op_sel_hi:[1,0]
	v_pk_mul_f32 v[58:59], v[14:15], v[62:63] op_sel_hi:[1,0]
	v_pk_mul_f32 v[60:61], v[16:17], v[62:63] op_sel_hi:[1,0]
	ds_write_b128 v84, v[2:5] offset:3072
	v_cndmask_b32_e64 v5, v45, v57, s[40:41]
	v_cndmask_b32_e64 v4, v44, v56, s[40:41]
	v_cndmask_b32_e64 v3, v43, v55, s[40:41]
	v_cndmask_b32_e64 v2, v42, v54, s[40:41]
	v_pk_mul_f32 v[46:47], v[46:47], v[64:65] op_sel_hi:[1,0]
	v_pk_mul_f32 v[48:49], v[48:49], v[64:65] op_sel_hi:[1,0]
	v_pk_mul_f32 v[38:39], v[38:39], v[62:63] op_sel_hi:[1,0]
	v_pk_mul_f32 v[82:83], v[40:41], v[62:63] op_sel_hi:[1,0]
	v_cndmask_b32_e64 v17, v61, v53, s[40:41]
	v_cndmask_b32_e64 v16, v60, v52, s[40:41]
	v_cndmask_b32_e64 v15, v59, v51, s[40:41]
	v_cndmask_b32_e64 v14, v58, v50, s[40:41]
	ds_write_b128 v84, v[2:5] offset:4096
	v_cndmask_b32_e64 v5, v83, v49, s[40:41]
	v_cndmask_b32_e64 v4, v82, v48, s[40:41]
	v_cndmask_b32_e64 v3, v39, v47, s[40:41]
	v_cndmask_b32_e64 v2, v38, v46, s[40:41]
	v_pk_mul_f32 v[30:31], v[30:31], v[64:65] op_sel_hi:[1,0]
	v_pk_mul_f32 v[32:33], v[32:33], v[64:65] op_sel_hi:[1,0]
	v_pk_mul_f32 v[26:27], v[26:27], v[62:63] op_sel_hi:[1,0]
	v_pk_mul_f32 v[28:29], v[28:29], v[62:63] op_sel_hi:[1,0]
	ds_write_b128 v84, v[14:17] offset:1024
	v_pk_mul_f32 v[14:15], v[34:35], v[64:65] op_sel_hi:[1,0]
	v_pk_mul_f32 v[16:17], v[36:37], v[64:65] op_sel_hi:[1,0]
	v_pk_mul_f32 v[34:35], v[6:7], v[62:63] op_sel_hi:[1,0]
	v_pk_mul_f32 v[36:37], v[8:9], v[62:63] op_sel_hi:[1,0]
	ds_write_b128 v84, v[2:5] offset:5120
	v_cndmask_b32_e64 v5, v29, v33, s[40:41]
	v_cndmask_b32_e64 v4, v28, v32, s[40:41]
	v_cndmask_b32_e64 v3, v27, v31, s[40:41]
	v_cndmask_b32_e64 v2, v26, v30, s[40:41]
	v_pk_mul_f32 v[22:23], v[22:23], v[64:65] op_sel_hi:[1,0]
	v_pk_mul_f32 v[24:25], v[24:25], v[64:65] op_sel_hi:[1,0]
	v_pk_mul_f32 v[64:65], v[18:19], v[62:63] op_sel_hi:[1,0]
	v_pk_mul_f32 v[62:63], v[20:21], v[62:63] op_sel_hi:[1,0]
	ds_write_b128 v84, v[2:5] offset:6144
	v_cndmask_b32_e64 v5, v63, v25, s[40:41]
	v_cndmask_b32_e64 v4, v62, v24, s[40:41]
	v_cndmask_b32_e64 v3, v65, v23, s[40:41]
	v_cndmask_b32_e64 v2, v64, v22, s[40:41]
	ds_write_b128 v84, v[2:5] offset:7168
	v_lshlrev_b32_e32 v2, 9, v182
	v_cndmask_b32_e64 v9, v37, v17, s[40:41]
	v_cndmask_b32_e64 v8, v36, v16, s[40:41]
	v_cndmask_b32_e64 v7, v35, v15, s[40:41]
	v_cndmask_b32_e64 v6, v34, v14, s[40:41]
	v_bitop3_b32 v2, v2, s6, v181 bitop3:0x36
	ds_write_b128 v84, v[6:9] offset:2048
	v_lshl_add_u32 v84, v2, 4, 0
	s_waitcnt lgkmcnt(0)
	s_barrier
	s_add_u32 s100, s100, s14
	s_addc_u32 s101, s101, s15
	v_lshlrev_b32_e32 v132, 4, v178
	global_load_dwordx4 v[100:103], v132, s[100:101]
	global_load_dwordx4 v[104:107], v132, s[100:101] offset:64
	global_load_dwordx4 v[108:111], v132, s[100:101] offset:128
	global_load_dwordx4 v[112:115], v132, s[100:101] offset:192
	global_load_dwordx4 v[116:119], v132, s[100:101] offset:256
	global_load_dwordx4 v[120:123], v132, s[100:101] offset:320
	global_load_dwordx4 v[124:127], v132, s[100:101] offset:384
	global_load_dwordx4 v[128:131], v132, s[100:101] offset:448
	ds_read_b128 v[2:5], v84
	ds_read_b128 v[6:9], v84 offset:1024
	v_cndmask_b32_e64 v67, v67, v71, s[40:41]
	v_cndmask_b32_e64 v66, v66, v70, s[40:41]
	v_cndmask_b32_e64 v69, v69, v73, s[40:41]
	v_cndmask_b32_e64 v68, v68, v72, s[40:41]
	v_cndmask_b32_e64 v73, v75, v79, s[40:41]
	v_cndmask_b32_e64 v72, v74, v78, s[40:41]
	v_cndmask_b32_e64 v75, v77, v81, s[40:41]
	v_cndmask_b32_e64 v74, v76, v80, s[40:41]
	v_cndmask_b32_e64 v77, v47, v39, s[40:41]
	v_cndmask_b32_e64 v76, v46, v38, s[40:41]
	s_waitcnt lgkmcnt(1)
	v_pk_add_f32 v[38:39], v[66:67], v[2:3]
	v_cndmask_b32_e64 v71, v17, v37, s[40:41]
	v_mul_f32_e32 v66, v39, v39
	v_cndmask_b32_e64 v70, v16, v36, s[40:41]
	v_pk_add_f32 v[36:37], v[68:69], v[4:5]
	v_fmac_f32_e32 v66, v38, v38
	v_cndmask_b32_e64 v59, v51, v59, s[40:41]
	v_cndmask_b32_e64 v58, v50, v58, s[40:41]
	ds_read_b128 v[10:13], v84 offset:2048
	v_fmac_f32_e32 v66, v36, v36
	v_cndmask_b32_e64 v53, v53, v61, s[40:41]
	v_cndmask_b32_e64 v52, v52, v60, s[40:41]
	v_cndmask_b32_e64 v61, v15, v35, s[40:41]
	v_cndmask_b32_e64 v60, v14, v34, s[40:41]
	v_fmac_f32_e32 v66, v37, v37
	s_waitcnt lgkmcnt(1)
	v_pk_add_f32 v[34:35], v[58:59], v[6:7]
	v_cndmask_b32_e64 v79, v49, v83, s[40:41]
	v_fmac_f32_e32 v66, v34, v34
	v_cndmask_b32_e64 v78, v48, v82, s[40:41]
	v_cndmask_b32_e64 v83, v33, v29, s[40:41]
	v_cndmask_b32_e64 v82, v32, v28, s[40:41]
	v_pk_add_f32 v[32:33], v[52:53], v[8:9]
	v_fmac_f32_e32 v66, v35, v35
	ds_read_b128 v[14:17], v84 offset:3072
	v_fmac_f32_e32 v66, v32, v32
	v_cndmask_b32_e64 v81, v31, v27, s[40:41]
	v_cndmask_b32_e64 v80, v30, v26, s[40:41]
	v_fmac_f32_e32 v66, v33, v33
	s_waitcnt lgkmcnt(1)
	v_pk_add_f32 v[30:31], v[60:61], v[10:11]
	v_pk_add_f32 v[28:29], v[70:71], v[12:13]
	v_fmac_f32_e32 v66, v30, v30
	v_fmac_f32_e32 v66, v31, v31
	ds_read_b128 v[18:21], v84 offset:4096
	v_fmac_f32_e32 v66, v28, v28
	v_fmac_f32_e32 v66, v29, v29
	s_waitcnt lgkmcnt(1)
	v_pk_add_f32 v[26:27], v[72:73], v[14:15]
	v_cndmask_b32_e64 v63, v25, v63, s[40:41]
	v_fmac_f32_e32 v66, v26, v26
	v_cndmask_b32_e64 v62, v24, v62, s[40:41]
	v_pk_add_f32 v[24:25], v[74:75], v[16:17]
	v_fmac_f32_e32 v66, v27, v27
	v_cndmask_b32_e64 v55, v55, v43, s[40:41]
	v_cndmask_b32_e64 v54, v54, v42, s[40:41]
	ds_read_b128 v[40:43], v84 offset:5120
	v_fmac_f32_e32 v66, v24, v24
	v_cndmask_b32_e64 v65, v23, v65, s[40:41]
	v_cndmask_b32_e64 v64, v22, v64, s[40:41]
	v_fmac_f32_e32 v66, v25, v25
	s_waitcnt lgkmcnt(1)
	v_pk_add_f32 v[22:23], v[54:55], v[18:19]
	v_cndmask_b32_e64 v57, v57, v45, s[40:41]
	v_cndmask_b32_e64 v56, v56, v44, s[40:41]
	v_fmac_f32_e32 v66, v22, v22
	ds_read_b128 v[44:47], v84 offset:6144
	ds_read_b128 v[48:51], v84 offset:7168
	v_pk_add_f32 v[20:21], v[56:57], v[20:21]
	v_fmac_f32_e32 v66, v23, v23
	v_fmac_f32_e32 v66, v20, v20
	v_fmac_f32_e32 v66, v21, v21
	s_waitcnt lgkmcnt(2)
	v_pk_add_f32 v[18:19], v[76:77], v[40:41]
	v_pk_add_f32 v[16:17], v[78:79], v[42:43]
	v_fmac_f32_e32 v66, v18, v18
	v_fmac_f32_e32 v66, v19, v19
	v_fmac_f32_e32 v66, v16, v16
	s_waitcnt lgkmcnt(1)
	v_pk_add_f32 v[14:15], v[80:81], v[44:45]
	v_fmac_f32_e32 v66, v17, v17
	v_pk_mul_f32 v[4:5], v[14:15], v[14:15]
	v_pk_add_f32 v[12:13], v[82:83], v[46:47]
	v_add_f32_e32 v4, v4, v66
	v_pk_mul_f32 v[2:3], v[12:13], v[12:13]
	v_add_f32_e32 v4, v5, v4
	v_add_f32_e32 v2, v2, v4
	s_waitcnt lgkmcnt(0)
	v_pk_add_f32 v[8:9], v[64:65], v[48:49]
	v_add_f32_e32 v10, v3, v2
	v_pk_mul_f32 v[4:5], v[8:9], v[8:9]
	v_pk_add_f32 v[6:7], v[62:63], v[50:51]
	v_add_f32_e32 v4, v4, v10
	v_pk_mul_f32 v[2:3], v[6:7], v[6:7]
	v_add_f32_e32 v4, v5, v4
	v_add_f32_e32 v2, v2, v4
	v_add_f32_e32 v2, v3, v2
	ds_bpermute_b32 v3, v176, v2
	s_load_dwordx2 s[10:11], s[44:45], 0x80
	v_lshlrev_b32_e32 v4, 3, v178
	v_mov_b32_e32 v5, v0
	s_mov_b32 s6, 0x18a10000
	s_waitcnt lgkmcnt(0)
	v_add_f32_e32 v2, v2, v3
	ds_bpermute_b32 v1, v1, v2
	s_add_u32 s10, s10, s14
	s_addc_u32 s11, s11, s15
	s_mov_b64 s[14:15], 0x18a10000
	v_lshlrev_b32_e32 v44, 4, v178
	s_waitcnt lgkmcnt(0)
	v_add_f32_e32 v1, v2, v1
	v_fmamk_f32 v1, v1, 0x3c000000, v234
	v_cmp_gt_f32_e32 vcc, s90, v1
	v_mul_f32_e32 v2, 0x4b800000, v1
	s_nop 0
	v_cndmask_b32_e32 v1, v1, v2, vcc
	v_rsq_f32_e32 v1, v1
	s_nop 0
	v_mul_f32_e32 v2, 0x45800000, v1
	v_cndmask_b32_e32 v1, v1, v2, vcc
	v_lshlrev_b32_e32 v2, 4, v179
	v_or3_b32 v2, v2, v177, v180
	v_ashrrev_i32_e32 v3, 31, v2
	v_lshlrev_b64 v[2:3], 11, v[2:3]
	v_lshl_add_u64 v[2:3], s[42:43], 0, v[2:3]
	v_lshl_add_u64 v[2:3], v[2:3], 0, s[30:31]
	v_lshl_add_u64 v[2:3], v[2:3], 0, v[4:5]
	v_add_co_u32_e32 v40, vcc, s6, v2
	v_lshl_add_u64 v[10:11], v[2:3], 0, s[14:15]
	s_nop 0
	v_addc_co_u32_e32 v41, vcc, 0, v3, vcc
	v_mul_f32_e32 v1, v227, v1
	v_mul_f32_e32 v38, v38, v1
	v_mul_f32_e32 v36, v36, v1
	v_mul_f32_e32 v34, v34, v1
	v_mul_f32_e32 v32, v32, v1
	v_mul_f32_e32 v30, v30, v1
	v_mul_f32_e32 v28, v28, v1
	v_mul_f32_e32 v26, v26, v1
	v_mul_f32_e32 v24, v24, v1
	v_mul_f32_e32 v22, v22, v1
	v_mul_f32_e32 v20, v20, v1
	v_mul_f32_e32 v18, v18, v1
	v_mul_f32_e32 v16, v16, v1
	v_mul_f32_e32 v14, v14, v1
	v_mul_f32_e32 v12, v12, v1
	s_waitcnt vmcnt(0)
	v_readfirstlane_b32 s101, v224
	v_mov_b32_e32 v42, v146
	v_mov_b32_e32 v43, v147
	v_mov_b32_e32 v2, v100
	v_mov_b32_e32 v3, v101
	v_mov_b32_e32 v4, v102
	v_mov_b32_e32 v5, v103
	v_mul_f32_e32 v2, v2, v38
	v_lshlrev_b32_e32 v38, 16, v42
	v_mul_f32_e32 v2, v2, v38
	v_mul_f32_e32 v38, v39, v1
	v_mul_f32_e32 v4, v4, v36
	v_lshlrev_b32_e32 v36, 16, v43
	v_mul_f32_e32 v3, v3, v38
	v_and_b32_e32 v38, 0xffff0000, v42
	v_mul_f32_e32 v4, v4, v36
	v_mul_f32_e32 v36, v37, v1
	v_mul_f32_e32 v3, v3, v38
	v_mul_f32_e32 v5, v5, v36
	v_and_b32_e32 v36, 0xffff0000, v43
	v_mul_f32_e32 v5, v5, v36
	s_nop 1
	v_cvt_pk_bf16_f32 v2, v2, v3
	s_nop 1
	v_cvt_pk_bf16_f32 v3, v4, v5
	global_store_dwordx2 v[40:41], v[2:3], off
	v_mov_b32_e32 v36, v148
	v_mov_b32_e32 v37, v149
	s_nop 0
	v_mov_b32_e32 v2, v104
	v_mov_b32_e32 v3, v105
	v_mov_b32_e32 v4, v106
	v_mov_b32_e32 v5, v107
	v_mul_f32_e32 v2, v2, v34
	v_lshlrev_b32_e32 v34, 16, v36
	v_mul_f32_e32 v2, v2, v34
	v_mul_f32_e32 v34, v35, v1
	v_mul_f32_e32 v4, v4, v32
	v_lshlrev_b32_e32 v32, 16, v37
	v_mul_f32_e32 v3, v3, v34
	v_and_b32_e32 v34, 0xffff0000, v36
	v_mul_f32_e32 v4, v4, v32
	v_mul_f32_e32 v32, v33, v1
	v_mul_f32_e32 v3, v3, v34
	v_mul_f32_e32 v5, v5, v32
	v_and_b32_e32 v32, 0xffff0000, v37
	v_mul_f32_e32 v5, v5, v32
	s_nop 1
	v_cvt_pk_bf16_f32 v2, v2, v3
	s_nop 1
	v_cvt_pk_bf16_f32 v3, v4, v5
	global_store_dwordx2 v[10:11], v[2:3], off offset:32
	v_mov_b32_e32 v32, v150
	v_mov_b32_e32 v33, v151
	s_nop 0
	v_mov_b32_e32 v2, v108
	v_mov_b32_e32 v3, v109
	v_mov_b32_e32 v4, v110
	v_mov_b32_e32 v5, v111
	v_mul_f32_e32 v2, v2, v30
	v_lshlrev_b32_e32 v30, 16, v32
	v_mul_f32_e32 v2, v2, v30
	v_mul_f32_e32 v30, v31, v1
	v_mul_f32_e32 v4, v4, v28
	v_lshlrev_b32_e32 v28, 16, v33
	v_mul_f32_e32 v3, v3, v30
	v_and_b32_e32 v30, 0xffff0000, v32
	v_mul_f32_e32 v4, v4, v28
	v_mul_f32_e32 v28, v29, v1
	v_mul_f32_e32 v3, v3, v30
	v_mul_f32_e32 v5, v5, v28
	v_and_b32_e32 v28, 0xffff0000, v33
	v_mul_f32_e32 v5, v5, v28
	s_nop 1
	v_cvt_pk_bf16_f32 v2, v2, v3
	s_nop 1
	v_cvt_pk_bf16_f32 v3, v4, v5
	global_store_dwordx2 v[10:11], v[2:3], off offset:64
	v_mov_b32_e32 v28, v152
	v_mov_b32_e32 v29, v153
	s_nop 0
	v_mov_b32_e32 v2, v112
	v_mov_b32_e32 v3, v113
	v_mov_b32_e32 v4, v114
	v_mov_b32_e32 v5, v115
	v_mul_f32_e32 v2, v2, v26
	v_lshlrev_b32_e32 v26, 16, v28
	v_mul_f32_e32 v2, v2, v26
	v_mul_f32_e32 v26, v27, v1
	v_mul_f32_e32 v4, v4, v24
	v_lshlrev_b32_e32 v24, 16, v29
	v_mul_f32_e32 v3, v3, v26
	v_and_b32_e32 v26, 0xffff0000, v28
	v_mul_f32_e32 v4, v4, v24
	v_mul_f32_e32 v24, v25, v1
	v_mul_f32_e32 v3, v3, v26
	v_mul_f32_e32 v5, v5, v24
	v_and_b32_e32 v24, 0xffff0000, v29
	v_mul_f32_e32 v5, v5, v24
	s_nop 1
	v_cvt_pk_bf16_f32 v2, v2, v3
	s_nop 1
	v_cvt_pk_bf16_f32 v3, v4, v5
	global_store_dwordx2 v[10:11], v[2:3], off offset:96
	v_mov_b32_e32 v24, v188
	v_mov_b32_e32 v25, v189
	s_nop 0
	v_mov_b32_e32 v2, v116
	v_mov_b32_e32 v3, v117
	v_mov_b32_e32 v4, v118
	v_mov_b32_e32 v5, v119
	v_mul_f32_e32 v2, v2, v22
	v_lshlrev_b32_e32 v22, 16, v24
	v_mul_f32_e32 v2, v2, v22
	v_mul_f32_e32 v22, v23, v1
	v_mul_f32_e32 v4, v4, v20
	v_lshlrev_b32_e32 v20, 16, v25
	v_mul_f32_e32 v3, v3, v22
	v_and_b32_e32 v22, 0xffff0000, v24
	v_mul_f32_e32 v4, v4, v20
	v_mul_f32_e32 v20, v21, v1
	v_mul_f32_e32 v3, v3, v22
	v_mul_f32_e32 v5, v5, v20
	v_and_b32_e32 v20, 0xffff0000, v25
	v_mul_f32_e32 v5, v5, v20
	s_nop 1
	v_cvt_pk_bf16_f32 v2, v2, v3
	s_nop 1
	v_cvt_pk_bf16_f32 v3, v4, v5
	global_store_dwordx2 v[10:11], v[2:3], off offset:128
	v_mov_b32_e32 v20, v190
	v_mov_b32_e32 v21, v191
	s_nop 0
	v_mov_b32_e32 v2, v120
	v_mov_b32_e32 v3, v121
	v_mov_b32_e32 v4, v122
	v_mov_b32_e32 v5, v123
	v_mul_f32_e32 v2, v2, v18
	v_lshlrev_b32_e32 v18, 16, v20
	v_mul_f32_e32 v2, v2, v18
	v_mul_f32_e32 v18, v19, v1
	v_mul_f32_e32 v4, v4, v16
	v_lshlrev_b32_e32 v16, 16, v21
	v_mul_f32_e32 v3, v3, v18
	v_and_b32_e32 v18, 0xffff0000, v20
	v_mul_f32_e32 v4, v4, v16
	v_mul_f32_e32 v16, v17, v1
	v_mul_f32_e32 v3, v3, v18
	v_mul_f32_e32 v5, v5, v16
	v_and_b32_e32 v16, 0xffff0000, v21
	v_mul_f32_e32 v5, v5, v16
	s_nop 1
	v_cvt_pk_bf16_f32 v2, v2, v3
	s_nop 1
	v_cvt_pk_bf16_f32 v3, v4, v5
	global_store_dwordx2 v[10:11], v[2:3], off offset:160
	v_mov_b32_e32 v16, v192
	v_mov_b32_e32 v17, v193
	s_nop 0
	v_mov_b32_e32 v2, v124
	v_mov_b32_e32 v3, v125
	v_mov_b32_e32 v4, v126
	v_mov_b32_e32 v5, v127
	v_mul_f32_e32 v2, v2, v14
	v_lshlrev_b32_e32 v14, 16, v16
	v_mul_f32_e32 v2, v2, v14
	v_mul_f32_e32 v14, v15, v1
	v_mul_f32_e32 v4, v4, v12
	v_lshlrev_b32_e32 v12, 16, v17
	v_mul_f32_e32 v3, v3, v14
	v_and_b32_e32 v14, 0xffff0000, v16
	v_mul_f32_e32 v4, v4, v12
	v_mul_f32_e32 v12, v13, v1
	v_mul_f32_e32 v3, v3, v14
	v_mul_f32_e32 v5, v5, v12
	v_and_b32_e32 v12, 0xffff0000, v17
	v_mul_f32_e32 v5, v5, v12
	s_nop 1
	v_cvt_pk_bf16_f32 v2, v2, v3
	s_nop 1
	v_cvt_pk_bf16_f32 v3, v4, v5
	global_store_dwordx2 v[10:11], v[2:3], off offset:192
	v_mov_b32_e32 v2, v194
	v_mov_b32_e32 v3, v195
	s_nop 0
	v_mov_b32_e32 v12, v128
	v_mov_b32_e32 v13, v129
	v_mov_b32_e32 v14, v130
	v_mov_b32_e32 v15, v131
	v_mul_f32_e32 v4, v8, v1
	v_lshlrev_b32_e32 v5, 16, v2
	v_mul_f32_e32 v4, v4, v12
	v_mul_f32_e32 v4, v4, v5
	v_mul_f32_e32 v5, v9, v1
	v_mul_f32_e32 v5, v5, v13
	v_and_b32_e32 v2, 0xffff0000, v2
	v_mul_f32_e32 v2, v5, v2
	v_mul_f32_e32 v5, v6, v1
	v_mul_f32_e32 v1, v7, v1
	v_mul_f32_e32 v5, v5, v14
	v_lshlrev_b32_e32 v6, 16, v3
	v_mul_f32_e32 v1, v1, v15
	v_and_b32_e32 v3, 0xffff0000, v3
	v_mul_f32_e32 v5, v5, v6
	v_mul_f32_e32 v1, v1, v3
	s_nop 1
	v_cvt_pk_bf16_f32 v2, v4, v2
	s_nop 1
	v_cvt_pk_bf16_f32 v3, v5, v1
	global_store_dwordx2 v[10:11], v[2:3], off offset:224
	s_barrier
